# DeltaNet prep gate cumulative sum: six ds_bpermute shuffle rounds replaced by an in-register DPP scan (row_shr 1/2/4/8 + row_bcast 15/31), as the mLSTM gate scan already does
# baseline (speedup 1.0000x reference)
.LBB0_527:
	s_or_b64 exec, exec, s[14:15]
	v_mul_f32_e32 v0, 0x3fb8aa3b, v0
	v_exp_f32_e32 v0, v0
	v_mov_b32_e32 v4, 0
	v_mov_b32_e32 v5, 0
	v_mul_f32_e64 v0, v2, -v0
	s_nop 1
	v_add_f32_dpp v0, v0, v0 row_shr:1 row_mask:0xf bank_mask:0xf bound_ctrl:1
	s_nop 1
	v_add_f32_dpp v0, v0, v0 row_shr:2 row_mask:0xf bank_mask:0xf bound_ctrl:1
	s_nop 1
	v_add_f32_dpp v0, v0, v0 row_shr:4 row_mask:0xf bank_mask:0xf bound_ctrl:1
	s_nop 1
	v_add_f32_dpp v0, v0, v0 row_shr:8 row_mask:0xf bank_mask:0xf bound_ctrl:1
	s_nop 1
	v_mov_b32_dpp v4, v0 row_bcast:15 row_mask:0xa bank_mask:0xf
	v_add_f32_e32 v0, v0, v4
	s_nop 1
	v_mov_b32_dpp v5, v0 row_bcast:31 row_mask:0xc bank_mask:0xf
	v_add_f32_e32 v0, v0, v5
	v_lshl_add_u32 v3, v81, 2, 0
	v_add_u32_e32 v4, 0x15c00, v3
	v_lshlrev_b32_e32 v41, 16, v41
	v_mul_f32_e32 v2, 0xbfb8aa3b, v41
	v_exp_f32_e32 v2, v2
	v_cmp_eq_u32_e64 s[10:11], 63, v81
	v_add_f32_e32 v2, 1.0, v2
	v_rcp_f32_e32 v2, v2
	ds_write_b32 v4, v2
	v_add_u32_e32 v2, 0x15d00, v3
	ds_write_b32 v2, v0
	v_mul_f32_e32 v0, 0x3fb8aa3b, v0
	v_exp_f32_e32 v0, v0
	v_add_u32_e32 v2, 0x15e00, v3
	ds_write_b32 v2, v0
	s_and_b64 exec, exec, s[10:11]
	s_cbranch_execz .LBB0_529
	s_lshl_b64 s[10:11], s[36:37], 2
	s_add_u32 s10, s40, s10
	s_addc_u32 s11, s41, s11
	global_store_dword v1, v0, s[10:11]
